# v11_gatent
# speedup vs baseline: 1.0459x; 1.0049x over previous
; __device__ __forceinline__ void unpack8(const u32x4 w, f32x4& lo, f32x4& hi) { lo = (f32x4){bf_lo(w.x), bf_hi(w.x), bf_lo(w.y), bf_hi(w.y)}; hi = (f32x4){bf_lo(w.z), bf_hi(w.z), bf_lo(w.w), bf_hi(w.w)}; }
;     __device__ __forceinline__ void operator()(AccT& acc, const Unit& u, int wr, int wc, int fr, int fq) const {
;         const int row0 = u.pm * 256 + wr * 64 + fr, col0 = u.pn * 256 + wc * 32 + 8 * fq;
;         constexpr float TINY = 1e-30f;
; #pragma unroll
;         for (int ai = 0; ai < 2; ++ai)
; #pragma unroll
;             for (int m = 0; m < 4; ++m) { const size_t row = (size_t)(row0 + ai * 128 + m * 16);
; #pragma unroll
;                 for (int bj = 0; bj < 2; ++bj) { f32x4 p0, p1; unpack8(*(const u32x4*)(PROJ + row * DIN + 8192 + col0 + bj * 128), p0, p1);
; #pragma unroll
;                     for (int j = 0; j < 4; ++j) { p0[j] = fmaxf(p0[j], TINY); p1[j] = fmaxf(p1[j], TINY); }
;                     if (u.kind == 0) { f32x4 s0, s1; unpack8(*(const u32x4*)(PROJ + row * DIN + 4096 + col0 + bj * 128), s0, s1);
; #pragma unroll
;                         for (int j = 0; j < 4; ++j) { acc[ai][bj][m][0][j] *= s0[j] * __builtin_amdgcn_rcpf(p0[j]); acc[ai][bj][m][1][j] *= s1[j] * __builtin_amdgcn_rcpf(p1[j]); } }
.LBB0_488:
	v_mov_b32_e32 v133, v254
	s_lshl_b32 s4, s66, 8
	v_lshrrev_b32_e32 v132, 1, v133
	v_and_or_b32 v132, v132, 24, s4
	v_and_or_b32 v133, v133, 15, s83
	v_or_b32_e32 v132, s84, v132
	v_lshl_add_u32 v134, s3, 8, v133
	v_mov_b64_e32 v[136:137], s[20:21]
	v_ashrrev_i32_e32 v133, 31, v132
	v_mad_i64_i32 v[136:137], s[4:5], v134, s78, v[136:137]
	v_lshl_add_u64 v[136:137], v[132:133], 1, v[136:137]
	v_add_co_u32_e32 v138, vcc, s77, v136
	v_ashrrev_i32_e32 v135, 31, v134
	s_nop 0
	v_addc_co_u32_e32 v139, vcc, 0, v137, vcc
	s_cmp_lg_u32 s8, 0
	v_lshlrev_b64 v[138:139], 13, v[134:135]
	s_cselect_b64 s[16:17], -1, 0
	v_lshl_add_u64 v[138:139], s[26:27], 0, v[138:139]
	s_and_b64 vcc, exec, s[16:17]
	v_lshl_add_u64 v[138:139], v[132:133], 1, v[138:139]
	s_mov_b64 s[4:5], 0x4000
	v_lshl_add_u64 v[226:227], v[136:137], 0, s[4:5]
	global_load_dwordx4 v[162:165], v[226:227], off nt
	global_load_dwordx4 v[166:169], v[226:227], off offset:256 nt
	s_mov_b64 s[4:5], 0x64000
	v_lshl_add_u64 v[226:227], v[136:137], 0, s[4:5]
	global_load_dwordx4 v[170:173], v[226:227], off nt
	global_load_dwordx4 v[174:177], v[226:227], off offset:256 nt
	s_mov_b64 s[4:5], 0xc4000
	v_lshl_add_u64 v[226:227], v[136:137], 0, s[4:5]
	global_load_dwordx4 v[178:181], v[226:227], off nt
	global_load_dwordx4 v[182:185], v[226:227], off offset:256 nt
	s_mov_b64 s[4:5], 0x124000
	v_lshl_add_u64 v[226:227], v[136:137], 0, s[4:5]
	global_load_dwordx4 v[186:189], v[226:227], off nt
	global_load_dwordx4 v[190:193], v[226:227], off offset:256 nt
	s_mov_b64 s[4:5], 0x304000
	v_lshl_add_u64 v[226:227], v[136:137], 0, s[4:5]
	global_load_dwordx4 v[194:197], v[226:227], off nt
	global_load_dwordx4 v[198:201], v[226:227], off offset:256 nt
	s_mov_b64 s[4:5], 0x364000
	v_lshl_add_u64 v[226:227], v[136:137], 0, s[4:5]
	global_load_dwordx4 v[202:205], v[226:227], off nt
	global_load_dwordx4 v[206:209], v[226:227], off offset:256 nt
	s_mov_b64 s[4:5], 0x3c4000
	v_lshl_add_u64 v[226:227], v[136:137], 0, s[4:5]
	global_load_dwordx4 v[210:213], v[226:227], off nt
	global_load_dwordx4 v[214:217], v[226:227], off offset:256 nt
	s_mov_b64 s[4:5], 0x424000
	v_lshl_add_u64 v[226:227], v[136:137], 0, s[4:5]
	global_load_dwordx4 v[218:221], v[226:227], off nt
	global_load_dwordx4 v[222:225], v[226:227], off offset:256 nt
	s_cmp_lg_u32 s8, 0
	s_cbranch_scc1 .Lbr_kind1
	s_mov_b64 s[4:5], 0x2000
	v_lshl_add_u64 v[226:227], v[136:137], 0, s[4:5]
	global_load_dwordx4 v[228:231], v[226:227], off nt
	global_load_dwordx4 v[232:235], v[226:227], off offset:256 nt
	s_mov_b64 s[4:5], 0x62000
	v_lshl_add_u64 v[226:227], v[136:137], 0, s[4:5]
	global_load_dwordx4 v[236:239], v[226:227], off nt
	global_load_dwordx4 v[240:243], v[226:227], off offset:256 nt
	s_mov_b64 s[4:5], 0xc2000
	v_lshl_add_u64 v[226:227], v[136:137], 0, s[4:5]
	global_load_dwordx4 v[244:247], v[226:227], off nt
	global_load_dwordx4 v[248:251], v[226:227], off offset:256 nt
	s_waitcnt vmcnt(5)
	v_lshlrev_b32_e32 v140, 16, v162
	v_and_b32_e32 v141, 0xffff0000, v162
	v_lshlrev_b32_e32 v142, 16, v163
	v_and_b32_e32 v143, 0xffff0000, v163
	v_lshlrev_b32_e32 v144, 16, v164
	v_and_b32_e32 v145, 0xffff0000, v164
	v_lshlrev_b32_e32 v146, 16, v165
	v_and_b32_e32 v147, 0xffff0000, v165
	v_max_f32_e32 v140, v140, v140
	v_max_f32_e32 v141, v141, v141
	v_max_f32_e32 v142, v142, v142
	v_max_f32_e32 v143, v143, v143
	v_max_f32_e32 v144, v144, v144
	v_max_f32_e32 v145, v145, v145
	v_max_f32_e32 v146, v146, v146
	v_max_f32_e32 v147, v147, v147
	v_max_f32_e32 v140, 0xda24260, v140
	v_max_f32_e32 v141, 0xda24260, v141
	v_max_f32_e32 v142, 0xda24260, v142
	v_max_f32_e32 v143, 0xda24260, v143
	v_max_f32_e32 v144, 0xda24260, v144
	v_max_f32_e32 v145, 0xda24260, v145
	v_max_f32_e32 v146, 0xda24260, v146
	v_max_f32_e32 v147, 0xda24260, v147
	v_rcp_f32_e32 v140, v140
	v_rcp_f32_e32 v141, v141
	v_rcp_f32_e32 v142, v142
	v_rcp_f32_e32 v143, v143
	v_rcp_f32_e32 v144, v144
	v_rcp_f32_e32 v145, v145
	v_rcp_f32_e32 v146, v146
	v_rcp_f32_e32 v147, v147
	v_lshlrev_b32_e32 v154, 16, v228
	v_and_b32_e32 v155, 0xffff0000, v228
	v_lshlrev_b32_e32 v156, 16, v229
	v_and_b32_e32 v157, 0xffff0000, v229
	v_lshlrev_b32_e32 v158, 16, v230
	v_and_b32_e32 v159, 0xffff0000, v230
	v_lshlrev_b32_e32 v160, 16, v231
	v_and_b32_e32 v161, 0xffff0000, v231
	s_mov_b64 s[4:5], 0x122000
	v_lshl_add_u64 v[226:227], v[136:137], 0, s[4:5]
	global_load_dwordx4 v[162:165], v[226:227], off nt
	v_pk_mul_f32 v[140:141], v[140:141], v[154:155]
	v_pk_mul_f32 v[142:143], v[142:143], v[156:157]
	v_pk_mul_f32 v[144:145], v[144:145], v[158:159]
	v_pk_mul_f32 v[146:147], v[146:147], v[160:161]
	v_pk_mul_f32 v[124:125], v[124:125], v[140:141]
	v_pk_mul_f32 v[126:127], v[126:127], v[142:143]
	v_pk_mul_f32 v[120:121], v[120:121], v[144:145]
	v_pk_mul_f32 v[122:123], v[122:123], v[146:147]
	s_waitcnt vmcnt(5)
; __device__ __forceinline__ void unpack8(const u32x4 w, f32x4& lo, f32x4& hi) { lo = (f32x4){bf_lo(w.x), bf_hi(w.x), bf_lo(w.y), bf_hi(w.y)}; hi = (f32x4){bf_lo(w.z), bf_hi(w.z), bf_lo(w.w), bf_hi(w.w)}; }
;     __device__ __forceinline__ void operator()(AccT& acc, const Unit& u, int wr, int wc, int fr, int fq) const {
;     ...
;                 for (int bj = 0; bj < 2; ++bj) { f32x4 p0, p1; unpack8(*(const u32x4*)(PROJ + row * DIN + 8192 + col0 + bj * 128), p0, p1);
; #pragma unroll
;                     for (int j = 0; j < 4; ++j) { p0[j] = fmaxf(p0[j], TINY); p1[j] = fmaxf(p1[j], TINY); }
;                     if (u.kind == 0) { f32x4 s0, s1; unpack8(*(const u32x4*)(PROJ + row * DIN + 4096 + col0 + bj * 128), s0, s1);
; #pragma unroll
;                         for (int j = 0; j < 4; ++j) { acc[ai][bj][m][0][j] *= s0[j] * __builtin_amdgcn_rcpf(p0[j]); acc[ai][bj][m][1][j] *= s1[j] * __builtin_amdgcn_rcpf(p1[j]); } }
	v_lshlrev_b32_e32 v140, 16, v166
	v_and_b32_e32 v141, 0xffff0000, v166
	v_lshlrev_b32_e32 v142, 16, v167
	v_and_b32_e32 v143, 0xffff0000, v167
	v_lshlrev_b32_e32 v144, 16, v168
	v_and_b32_e32 v145, 0xffff0000, v168
	v_lshlrev_b32_e32 v146, 16, v169
	v_and_b32_e32 v147, 0xffff0000, v169
	v_max_f32_e32 v140, v140, v140
	v_max_f32_e32 v141, v141, v141
	v_max_f32_e32 v142, v142, v142
	v_max_f32_e32 v143, v143, v143
	v_max_f32_e32 v144, v144, v144
	v_max_f32_e32 v145, v145, v145
	v_max_f32_e32 v146, v146, v146
	v_max_f32_e32 v147, v147, v147
	v_max_f32_e32 v140, 0xda24260, v140
	v_max_f32_e32 v141, 0xda24260, v141
	v_max_f32_e32 v142, 0xda24260, v142
	v_max_f32_e32 v143, 0xda24260, v143
	v_max_f32_e32 v144, 0xda24260, v144
	v_max_f32_e32 v145, 0xda24260, v145
	v_max_f32_e32 v146, 0xda24260, v146
	v_max_f32_e32 v147, 0xda24260, v147
	v_rcp_f32_e32 v140, v140
	v_rcp_f32_e32 v141, v141
	v_rcp_f32_e32 v142, v142
	v_rcp_f32_e32 v143, v143
	v_rcp_f32_e32 v144, v144
	v_rcp_f32_e32 v145, v145
	v_rcp_f32_e32 v146, v146
	v_rcp_f32_e32 v147, v147
	v_lshlrev_b32_e32 v154, 16, v232
	v_and_b32_e32 v155, 0xffff0000, v232
	v_lshlrev_b32_e32 v156, 16, v233
	v_and_b32_e32 v157, 0xffff0000, v233
	v_lshlrev_b32_e32 v158, 16, v234
	v_and_b32_e32 v159, 0xffff0000, v234
	v_lshlrev_b32_e32 v160, 16, v235
	v_and_b32_e32 v161, 0xffff0000, v235
	global_load_dwordx4 v[166:169], v[226:227], off offset:256 nt
	v_pk_mul_f32 v[140:141], v[140:141], v[154:155]
	v_pk_mul_f32 v[142:143], v[142:143], v[156:157]
	v_pk_mul_f32 v[144:145], v[144:145], v[158:159]
	v_pk_mul_f32 v[146:147], v[146:147], v[160:161]
	v_pk_mul_f32 v[92:93], v[92:93], v[140:141]
	v_pk_mul_f32 v[94:95], v[94:95], v[142:143]
	v_pk_mul_f32 v[88:89], v[88:89], v[144:145]
	v_pk_mul_f32 v[90:91], v[90:91], v[146:147]
	s_waitcnt vmcnt(5)
	v_lshlrev_b32_e32 v140, 16, v170
	v_and_b32_e32 v141, 0xffff0000, v170
	v_lshlrev_b32_e32 v142, 16, v171
	v_and_b32_e32 v143, 0xffff0000, v171
	v_lshlrev_b32_e32 v144, 16, v172
	v_and_b32_e32 v145, 0xffff0000, v172
	v_lshlrev_b32_e32 v146, 16, v173
	v_and_b32_e32 v147, 0xffff0000, v173
	v_max_f32_e32 v140, v140, v140
	v_max_f32_e32 v141, v141, v141
	v_max_f32_e32 v142, v142, v142
	v_max_f32_e32 v143, v143, v143
	v_max_f32_e32 v144, v144, v144
	v_max_f32_e32 v145, v145, v145
	v_max_f32_e32 v146, v146, v146
	v_max_f32_e32 v147, v147, v147
	v_max_f32_e32 v140, 0xda24260, v140
	v_max_f32_e32 v141, 0xda24260, v141
	v_max_f32_e32 v142, 0xda24260, v142
	v_max_f32_e32 v143, 0xda24260, v143
	v_max_f32_e32 v144, 0xda24260, v144
	v_max_f32_e32 v145, 0xda24260, v145
	v_max_f32_e32 v146, 0xda24260, v146
	v_max_f32_e32 v147, 0xda24260, v147
	v_rcp_f32_e32 v140, v140
	v_rcp_f32_e32 v141, v141
	v_rcp_f32_e32 v142, v142
	v_rcp_f32_e32 v143, v143
	v_rcp_f32_e32 v144, v144
	v_rcp_f32_e32 v145, v145
	v_rcp_f32_e32 v146, v146
	v_rcp_f32_e32 v147, v147
	v_lshlrev_b32_e32 v154, 16, v236
	v_and_b32_e32 v155, 0xffff0000, v236
	v_lshlrev_b32_e32 v156, 16, v237
	v_and_b32_e32 v157, 0xffff0000, v237
	v_lshlrev_b32_e32 v158, 16, v238
	v_and_b32_e32 v159, 0xffff0000, v238
	v_lshlrev_b32_e32 v160, 16, v239
	v_and_b32_e32 v161, 0xffff0000, v239
	s_mov_b64 s[4:5], 0x302000
	v_lshl_add_u64 v[226:227], v[136:137], 0, s[4:5]
	global_load_dwordx4 v[170:173], v[226:227], off nt
	v_pk_mul_f32 v[140:141], v[140:141], v[154:155]
	v_pk_mul_f32 v[142:143], v[142:143], v[156:157]
	v_pk_mul_f32 v[144:145], v[144:145], v[158:159]
	v_pk_mul_f32 v[146:147], v[146:147], v[160:161]
	v_pk_mul_f32 v[116:117], v[116:117], v[140:141]
	v_pk_mul_f32 v[118:119], v[118:119], v[142:143]
	v_pk_mul_f32 v[112:113], v[112:113], v[144:145]
	v_pk_mul_f32 v[114:115], v[114:115], v[146:147]
	s_waitcnt vmcnt(5)
	v_lshlrev_b32_e32 v140, 16, v174
	v_and_b32_e32 v141, 0xffff0000, v174
	v_lshlrev_b32_e32 v142, 16, v175
	v_and_b32_e32 v143, 0xffff0000, v175
	v_lshlrev_b32_e32 v144, 16, v176
	v_and_b32_e32 v145, 0xffff0000, v176
	v_lshlrev_b32_e32 v146, 16, v177
	v_and_b32_e32 v147, 0xffff0000, v177
	v_max_f32_e32 v140, v140, v140
	v_max_f32_e32 v141, v141, v141
	v_max_f32_e32 v142, v142, v142
	v_max_f32_e32 v143, v143, v143
	v_max_f32_e32 v144, v144, v144
	v_max_f32_e32 v145, v145, v145
	v_max_f32_e32 v146, v146, v146
	v_max_f32_e32 v147, v147, v147
	v_max_f32_e32 v140, 0xda24260, v140
	v_max_f32_e32 v141, 0xda24260, v141
	v_max_f32_e32 v142, 0xda24260, v142
	v_max_f32_e32 v143, 0xda24260, v143
	v_max_f32_e32 v144, 0xda24260, v144
	v_max_f32_e32 v145, 0xda24260, v145
	v_max_f32_e32 v146, 0xda24260, v146
	v_max_f32_e32 v147, 0xda24260, v147
	v_rcp_f32_e32 v140, v140
	v_rcp_f32_e32 v141, v141
	v_rcp_f32_e32 v142, v142
	v_rcp_f32_e32 v143, v143
	v_rcp_f32_e32 v144, v144
	v_rcp_f32_e32 v145, v145
	v_rcp_f32_e32 v146, v146
	v_rcp_f32_e32 v147, v147
	v_lshlrev_b32_e32 v154, 16, v240
	v_and_b32_e32 v155, 0xffff0000, v240
	v_lshlrev_b32_e32 v156, 16, v241
	v_and_b32_e32 v157, 0xffff0000, v241
	v_lshlrev_b32_e32 v158, 16, v242
	v_and_b32_e32 v159, 0xffff0000, v242
	v_lshlrev_b32_e32 v160, 16, v243
	v_and_b32_e32 v161, 0xffff0000, v243
	global_load_dwordx4 v[174:177], v[226:227], off offset:256 nt
	v_pk_mul_f32 v[140:141], v[140:141], v[154:155]
	v_pk_mul_f32 v[142:143], v[142:143], v[156:157]
	v_pk_mul_f32 v[144:145], v[144:145], v[158:159]
	v_pk_mul_f32 v[146:147], v[146:147], v[160:161]
	v_pk_mul_f32 v[84:85], v[84:85], v[140:141]
	v_pk_mul_f32 v[86:87], v[86:87], v[142:143]
	v_pk_mul_f32 v[80:81], v[80:81], v[144:145]
	v_pk_mul_f32 v[82:83], v[82:83], v[146:147]
	s_waitcnt vmcnt(5)
; __device__ __forceinline__ void unpack8(const u32x4 w, f32x4& lo, f32x4& hi) { lo = (f32x4){bf_lo(w.x), bf_hi(w.x), bf_lo(w.y), bf_hi(w.y)}; hi = (f32x4){bf_lo(w.z), bf_hi(w.z), bf_lo(w.w), bf_hi(w.w)}; }
;     __device__ __forceinline__ void operator()(AccT& acc, const Unit& u, int wr, int wc, int fr, int fq) const {
;     ...
;                 for (int bj = 0; bj < 2; ++bj) { f32x4 p0, p1; unpack8(*(const u32x4*)(PROJ + row * DIN + 8192 + col0 + bj * 128), p0, p1);
; #pragma unroll
;                     for (int j = 0; j < 4; ++j) { p0[j] = fmaxf(p0[j], TINY); p1[j] = fmaxf(p1[j], TINY); }
;                     if (u.kind == 0) { f32x4 s0, s1; unpack8(*(const u32x4*)(PROJ + row * DIN + 4096 + col0 + bj * 128), s0, s1);
; #pragma unroll
;                         for (int j = 0; j < 4; ++j) { acc[ai][bj][m][0][j] *= s0[j] * __builtin_amdgcn_rcpf(p0[j]); acc[ai][bj][m][1][j] *= s1[j] * __builtin_amdgcn_rcpf(p1[j]); } }
	v_lshlrev_b32_e32 v140, 16, v178
	v_and_b32_e32 v141, 0xffff0000, v178
	v_lshlrev_b32_e32 v142, 16, v179
	v_and_b32_e32 v143, 0xffff0000, v179
	v_lshlrev_b32_e32 v144, 16, v180
	v_and_b32_e32 v145, 0xffff0000, v180
	v_lshlrev_b32_e32 v146, 16, v181
	v_and_b32_e32 v147, 0xffff0000, v181
	v_max_f32_e32 v140, v140, v140
	v_max_f32_e32 v141, v141, v141
	v_max_f32_e32 v142, v142, v142
	v_max_f32_e32 v143, v143, v143
	v_max_f32_e32 v144, v144, v144
	v_max_f32_e32 v145, v145, v145
	v_max_f32_e32 v146, v146, v146
	v_max_f32_e32 v147, v147, v147
	v_max_f32_e32 v140, 0xda24260, v140
	v_max_f32_e32 v141, 0xda24260, v141
	v_max_f32_e32 v142, 0xda24260, v142
	v_max_f32_e32 v143, 0xda24260, v143
	v_max_f32_e32 v144, 0xda24260, v144
	v_max_f32_e32 v145, 0xda24260, v145
	v_max_f32_e32 v146, 0xda24260, v146
	v_max_f32_e32 v147, 0xda24260, v147
	v_rcp_f32_e32 v140, v140
	v_rcp_f32_e32 v141, v141
	v_rcp_f32_e32 v142, v142
	v_rcp_f32_e32 v143, v143
	v_rcp_f32_e32 v144, v144
	v_rcp_f32_e32 v145, v145
	v_rcp_f32_e32 v146, v146
	v_rcp_f32_e32 v147, v147
	v_lshlrev_b32_e32 v154, 16, v244
	v_and_b32_e32 v155, 0xffff0000, v244
	v_lshlrev_b32_e32 v156, 16, v245
	v_and_b32_e32 v157, 0xffff0000, v245
	v_lshlrev_b32_e32 v158, 16, v246
	v_and_b32_e32 v159, 0xffff0000, v246
	v_lshlrev_b32_e32 v160, 16, v247
	v_and_b32_e32 v161, 0xffff0000, v247
	s_mov_b64 s[4:5], 0x362000
	v_lshl_add_u64 v[226:227], v[136:137], 0, s[4:5]
	global_load_dwordx4 v[178:181], v[226:227], off nt
	v_pk_mul_f32 v[140:141], v[140:141], v[154:155]
	v_pk_mul_f32 v[142:143], v[142:143], v[156:157]
	v_pk_mul_f32 v[144:145], v[144:145], v[158:159]
	v_pk_mul_f32 v[146:147], v[146:147], v[160:161]
	v_pk_mul_f32 v[108:109], v[108:109], v[140:141]
	v_pk_mul_f32 v[110:111], v[110:111], v[142:143]
	v_pk_mul_f32 v[104:105], v[104:105], v[144:145]
	v_pk_mul_f32 v[106:107], v[106:107], v[146:147]
	s_waitcnt vmcnt(5)
	v_lshlrev_b32_e32 v140, 16, v182
	v_and_b32_e32 v141, 0xffff0000, v182
	v_lshlrev_b32_e32 v142, 16, v183
	v_and_b32_e32 v143, 0xffff0000, v183
	v_lshlrev_b32_e32 v144, 16, v184
	v_and_b32_e32 v145, 0xffff0000, v184
	v_lshlrev_b32_e32 v146, 16, v185
	v_and_b32_e32 v147, 0xffff0000, v185
	v_max_f32_e32 v140, v140, v140
	v_max_f32_e32 v141, v141, v141
	v_max_f32_e32 v142, v142, v142
	v_max_f32_e32 v143, v143, v143
	v_max_f32_e32 v144, v144, v144
	v_max_f32_e32 v145, v145, v145
	v_max_f32_e32 v146, v146, v146
	v_max_f32_e32 v147, v147, v147
	v_max_f32_e32 v140, 0xda24260, v140
	v_max_f32_e32 v141, 0xda24260, v141
	v_max_f32_e32 v142, 0xda24260, v142
	v_max_f32_e32 v143, 0xda24260, v143
	v_max_f32_e32 v144, 0xda24260, v144
	v_max_f32_e32 v145, 0xda24260, v145
	v_max_f32_e32 v146, 0xda24260, v146
	v_max_f32_e32 v147, 0xda24260, v147
	v_rcp_f32_e32 v140, v140
	v_rcp_f32_e32 v141, v141
	v_rcp_f32_e32 v142, v142
	v_rcp_f32_e32 v143, v143
	v_rcp_f32_e32 v144, v144
	v_rcp_f32_e32 v145, v145
	v_rcp_f32_e32 v146, v146
	v_rcp_f32_e32 v147, v147
	v_lshlrev_b32_e32 v154, 16, v248
	v_and_b32_e32 v155, 0xffff0000, v248
	v_lshlrev_b32_e32 v156, 16, v249
	v_and_b32_e32 v157, 0xffff0000, v249
	v_lshlrev_b32_e32 v158, 16, v250
	v_and_b32_e32 v159, 0xffff0000, v250
	v_lshlrev_b32_e32 v160, 16, v251
	v_and_b32_e32 v161, 0xffff0000, v251
	global_load_dwordx4 v[182:185], v[226:227], off offset:256 nt
	v_pk_mul_f32 v[140:141], v[140:141], v[154:155]
	v_pk_mul_f32 v[142:143], v[142:143], v[156:157]
	v_pk_mul_f32 v[144:145], v[144:145], v[158:159]
	v_pk_mul_f32 v[146:147], v[146:147], v[160:161]
	v_pk_mul_f32 v[76:77], v[76:77], v[140:141]
	v_pk_mul_f32 v[78:79], v[78:79], v[142:143]
	v_pk_mul_f32 v[72:73], v[72:73], v[144:145]
	v_pk_mul_f32 v[74:75], v[74:75], v[146:147]
	s_waitcnt vmcnt(5)
	v_lshlrev_b32_e32 v140, 16, v186
	v_and_b32_e32 v141, 0xffff0000, v186
	v_lshlrev_b32_e32 v142, 16, v187
	v_and_b32_e32 v143, 0xffff0000, v187
	v_lshlrev_b32_e32 v144, 16, v188
	v_and_b32_e32 v145, 0xffff0000, v188
	v_lshlrev_b32_e32 v146, 16, v189
	v_and_b32_e32 v147, 0xffff0000, v189
	v_max_f32_e32 v140, v140, v140
	v_max_f32_e32 v141, v141, v141
	v_max_f32_e32 v142, v142, v142
	v_max_f32_e32 v143, v143, v143
	v_max_f32_e32 v144, v144, v144
	v_max_f32_e32 v145, v145, v145
	v_max_f32_e32 v146, v146, v146
	v_max_f32_e32 v147, v147, v147
	v_max_f32_e32 v140, 0xda24260, v140
	v_max_f32_e32 v141, 0xda24260, v141
	v_max_f32_e32 v142, 0xda24260, v142
	v_max_f32_e32 v143, 0xda24260, v143
	v_max_f32_e32 v144, 0xda24260, v144
	v_max_f32_e32 v145, 0xda24260, v145
	v_max_f32_e32 v146, 0xda24260, v146
	v_max_f32_e32 v147, 0xda24260, v147
	v_rcp_f32_e32 v140, v140
	v_rcp_f32_e32 v141, v141
	v_rcp_f32_e32 v142, v142
	v_rcp_f32_e32 v143, v143
	v_rcp_f32_e32 v144, v144
	v_rcp_f32_e32 v145, v145
	v_rcp_f32_e32 v146, v146
	v_rcp_f32_e32 v147, v147
	v_lshlrev_b32_e32 v154, 16, v162
	v_and_b32_e32 v155, 0xffff0000, v162
	v_lshlrev_b32_e32 v156, 16, v163
	v_and_b32_e32 v157, 0xffff0000, v163
	v_lshlrev_b32_e32 v158, 16, v164
	v_and_b32_e32 v159, 0xffff0000, v164
	v_lshlrev_b32_e32 v160, 16, v165
	v_and_b32_e32 v161, 0xffff0000, v165
	s_mov_b64 s[4:5], 0x3c2000
	v_lshl_add_u64 v[226:227], v[136:137], 0, s[4:5]
	global_load_dwordx4 v[186:189], v[226:227], off nt
	v_pk_mul_f32 v[140:141], v[140:141], v[154:155]
	v_pk_mul_f32 v[142:143], v[142:143], v[156:157]
	v_pk_mul_f32 v[144:145], v[144:145], v[158:159]
	v_pk_mul_f32 v[146:147], v[146:147], v[160:161]
	v_pk_mul_f32 v[100:101], v[100:101], v[140:141]
	v_pk_mul_f32 v[102:103], v[102:103], v[142:143]
	v_pk_mul_f32 v[96:97], v[96:97], v[144:145]
	v_pk_mul_f32 v[98:99], v[98:99], v[146:147]
	s_waitcnt vmcnt(5)
; __device__ __forceinline__ void unpack8(const u32x4 w, f32x4& lo, f32x4& hi) { lo = (f32x4){bf_lo(w.x), bf_hi(w.x), bf_lo(w.y), bf_hi(w.y)}; hi = (f32x4){bf_lo(w.z), bf_hi(w.z), bf_lo(w.w), bf_hi(w.w)}; }
;     __device__ __forceinline__ void operator()(AccT& acc, const Unit& u, int wr, int wc, int fr, int fq) const {
;     ...
;                 for (int bj = 0; bj < 2; ++bj) { f32x4 p0, p1; unpack8(*(const u32x4*)(PROJ + row * DIN + 8192 + col0 + bj * 128), p0, p1);
; #pragma unroll
;                     for (int j = 0; j < 4; ++j) { p0[j] = fmaxf(p0[j], TINY); p1[j] = fmaxf(p1[j], TINY); }
;                     if (u.kind == 0) { f32x4 s0, s1; unpack8(*(const u32x4*)(PROJ + row * DIN + 4096 + col0 + bj * 128), s0, s1);
; #pragma unroll
;                         for (int j = 0; j < 4; ++j) { acc[ai][bj][m][0][j] *= s0[j] * __builtin_amdgcn_rcpf(p0[j]); acc[ai][bj][m][1][j] *= s1[j] * __builtin_amdgcn_rcpf(p1[j]); } }
	v_lshlrev_b32_e32 v140, 16, v190
	v_and_b32_e32 v141, 0xffff0000, v190
	v_lshlrev_b32_e32 v142, 16, v191
	v_and_b32_e32 v143, 0xffff0000, v191
	v_lshlrev_b32_e32 v144, 16, v192
	v_and_b32_e32 v145, 0xffff0000, v192
	v_lshlrev_b32_e32 v146, 16, v193
	v_and_b32_e32 v147, 0xffff0000, v193
	v_max_f32_e32 v140, v140, v140
	v_max_f32_e32 v141, v141, v141
	v_max_f32_e32 v142, v142, v142
	v_max_f32_e32 v143, v143, v143
	v_max_f32_e32 v144, v144, v144
	v_max_f32_e32 v145, v145, v145
	v_max_f32_e32 v146, v146, v146
	v_max_f32_e32 v147, v147, v147
	v_max_f32_e32 v140, 0xda24260, v140
	v_max_f32_e32 v141, 0xda24260, v141
	v_max_f32_e32 v142, 0xda24260, v142
	v_max_f32_e32 v143, 0xda24260, v143
	v_max_f32_e32 v144, 0xda24260, v144
	v_max_f32_e32 v145, 0xda24260, v145
	v_max_f32_e32 v146, 0xda24260, v146
	v_max_f32_e32 v147, 0xda24260, v147
	v_rcp_f32_e32 v140, v140
	v_rcp_f32_e32 v141, v141
	v_rcp_f32_e32 v142, v142
	v_rcp_f32_e32 v143, v143
	v_rcp_f32_e32 v144, v144
	v_rcp_f32_e32 v145, v145
	v_rcp_f32_e32 v146, v146
	v_rcp_f32_e32 v147, v147
	v_lshlrev_b32_e32 v154, 16, v166
	v_and_b32_e32 v155, 0xffff0000, v166
	v_lshlrev_b32_e32 v156, 16, v167
	v_and_b32_e32 v157, 0xffff0000, v167
	v_lshlrev_b32_e32 v158, 16, v168
	v_and_b32_e32 v159, 0xffff0000, v168
	v_lshlrev_b32_e32 v160, 16, v169
	v_and_b32_e32 v161, 0xffff0000, v169
	global_load_dwordx4 v[190:193], v[226:227], off offset:256 nt
	v_pk_mul_f32 v[140:141], v[140:141], v[154:155]
	v_pk_mul_f32 v[142:143], v[142:143], v[156:157]
	v_pk_mul_f32 v[144:145], v[144:145], v[158:159]
	v_pk_mul_f32 v[146:147], v[146:147], v[160:161]
	v_pk_mul_f32 v[68:69], v[68:69], v[140:141]
	v_pk_mul_f32 v[70:71], v[70:71], v[142:143]
	v_pk_mul_f32 v[64:65], v[64:65], v[144:145]
	v_pk_mul_f32 v[66:67], v[66:67], v[146:147]
	s_waitcnt vmcnt(5)
	v_lshlrev_b32_e32 v140, 16, v194
	v_and_b32_e32 v141, 0xffff0000, v194
	v_lshlrev_b32_e32 v142, 16, v195
	v_and_b32_e32 v143, 0xffff0000, v195
	v_lshlrev_b32_e32 v144, 16, v196
	v_and_b32_e32 v145, 0xffff0000, v196
	v_lshlrev_b32_e32 v146, 16, v197
	v_and_b32_e32 v147, 0xffff0000, v197
	v_max_f32_e32 v140, v140, v140
	v_max_f32_e32 v141, v141, v141
	v_max_f32_e32 v142, v142, v142
	v_max_f32_e32 v143, v143, v143
	v_max_f32_e32 v144, v144, v144
	v_max_f32_e32 v145, v145, v145
	v_max_f32_e32 v146, v146, v146
	v_max_f32_e32 v147, v147, v147
	v_max_f32_e32 v140, 0xda24260, v140
	v_max_f32_e32 v141, 0xda24260, v141
	v_max_f32_e32 v142, 0xda24260, v142
	v_max_f32_e32 v143, 0xda24260, v143
	v_max_f32_e32 v144, 0xda24260, v144
	v_max_f32_e32 v145, 0xda24260, v145
	v_max_f32_e32 v146, 0xda24260, v146
	v_max_f32_e32 v147, 0xda24260, v147
	v_rcp_f32_e32 v140, v140
	v_rcp_f32_e32 v141, v141
	v_rcp_f32_e32 v142, v142
	v_rcp_f32_e32 v143, v143
	v_rcp_f32_e32 v144, v144
	v_rcp_f32_e32 v145, v145
	v_rcp_f32_e32 v146, v146
	v_rcp_f32_e32 v147, v147
	v_lshlrev_b32_e32 v154, 16, v170
	v_and_b32_e32 v155, 0xffff0000, v170
	v_lshlrev_b32_e32 v156, 16, v171
	v_and_b32_e32 v157, 0xffff0000, v171
	v_lshlrev_b32_e32 v158, 16, v172
	v_and_b32_e32 v159, 0xffff0000, v172
	v_lshlrev_b32_e32 v160, 16, v173
	v_and_b32_e32 v161, 0xffff0000, v173
	s_mov_b64 s[4:5], 0x422000
	v_lshl_add_u64 v[226:227], v[136:137], 0, s[4:5]
	global_load_dwordx4 v[194:197], v[226:227], off nt
	v_pk_mul_f32 v[140:141], v[140:141], v[154:155]
	v_pk_mul_f32 v[142:143], v[142:143], v[156:157]
	v_pk_mul_f32 v[144:145], v[144:145], v[158:159]
	v_pk_mul_f32 v[146:147], v[146:147], v[160:161]
	v_pk_mul_f32 v[60:61], v[60:61], v[140:141]
	v_pk_mul_f32 v[62:63], v[62:63], v[142:143]
	v_pk_mul_f32 v[56:57], v[56:57], v[144:145]
	v_pk_mul_f32 v[58:59], v[58:59], v[146:147]
	s_waitcnt vmcnt(5)
	v_lshlrev_b32_e32 v140, 16, v198
	v_and_b32_e32 v141, 0xffff0000, v198
	v_lshlrev_b32_e32 v142, 16, v199
	v_and_b32_e32 v143, 0xffff0000, v199
	v_lshlrev_b32_e32 v144, 16, v200
	v_and_b32_e32 v145, 0xffff0000, v200
	v_lshlrev_b32_e32 v146, 16, v201
	v_and_b32_e32 v147, 0xffff0000, v201
	v_max_f32_e32 v140, v140, v140
	v_max_f32_e32 v141, v141, v141
	v_max_f32_e32 v142, v142, v142
	v_max_f32_e32 v143, v143, v143
	v_max_f32_e32 v144, v144, v144
	v_max_f32_e32 v145, v145, v145
	v_max_f32_e32 v146, v146, v146
	v_max_f32_e32 v147, v147, v147
	v_max_f32_e32 v140, 0xda24260, v140
	v_max_f32_e32 v141, 0xda24260, v141
	v_max_f32_e32 v142, 0xda24260, v142
	v_max_f32_e32 v143, 0xda24260, v143
	v_max_f32_e32 v144, 0xda24260, v144
	v_max_f32_e32 v145, 0xda24260, v145
	v_max_f32_e32 v146, 0xda24260, v146
	v_max_f32_e32 v147, 0xda24260, v147
	v_rcp_f32_e32 v140, v140
	v_rcp_f32_e32 v141, v141
	v_rcp_f32_e32 v142, v142
	v_rcp_f32_e32 v143, v143
	v_rcp_f32_e32 v144, v144
	v_rcp_f32_e32 v145, v145
	v_rcp_f32_e32 v146, v146
	v_rcp_f32_e32 v147, v147
	v_lshlrev_b32_e32 v154, 16, v174
	v_and_b32_e32 v155, 0xffff0000, v174
	v_lshlrev_b32_e32 v156, 16, v175
	v_and_b32_e32 v157, 0xffff0000, v175
	v_lshlrev_b32_e32 v158, 16, v176
	v_and_b32_e32 v159, 0xffff0000, v176
	v_lshlrev_b32_e32 v160, 16, v177
	v_and_b32_e32 v161, 0xffff0000, v177
	global_load_dwordx4 v[198:201], v[226:227], off offset:256 nt
	v_pk_mul_f32 v[140:141], v[140:141], v[154:155]
	v_pk_mul_f32 v[142:143], v[142:143], v[156:157]
	v_pk_mul_f32 v[144:145], v[144:145], v[158:159]
	v_pk_mul_f32 v[146:147], v[146:147], v[160:161]
	v_pk_mul_f32 v[28:29], v[28:29], v[140:141]
	v_pk_mul_f32 v[30:31], v[30:31], v[142:143]
	v_pk_mul_f32 v[24:25], v[24:25], v[144:145]
	v_pk_mul_f32 v[26:27], v[26:27], v[146:147]
	s_waitcnt vmcnt(5)
; __device__ __forceinline__ void unpack8(const u32x4 w, f32x4& lo, f32x4& hi) { lo = (f32x4){bf_lo(w.x), bf_hi(w.x), bf_lo(w.y), bf_hi(w.y)}; hi = (f32x4){bf_lo(w.z), bf_hi(w.z), bf_lo(w.w), bf_hi(w.w)}; }
;     __device__ __forceinline__ void operator()(AccT& acc, const Unit& u, int wr, int wc, int fr, int fq) const {
;     ...
;                 for (int bj = 0; bj < 2; ++bj) { f32x4 p0, p1; unpack8(*(const u32x4*)(PROJ + row * DIN + 8192 + col0 + bj * 128), p0, p1);
; #pragma unroll
;                     for (int j = 0; j < 4; ++j) { p0[j] = fmaxf(p0[j], TINY); p1[j] = fmaxf(p1[j], TINY); }
;                     if (u.kind == 0) { f32x4 s0, s1; unpack8(*(const u32x4*)(PROJ + row * DIN + 4096 + col0 + bj * 128), s0, s1);
; #pragma unroll
;                         for (int j = 0; j < 4; ++j) { acc[ai][bj][m][0][j] *= s0[j] * __builtin_amdgcn_rcpf(p0[j]); acc[ai][bj][m][1][j] *= s1[j] * __builtin_amdgcn_rcpf(p1[j]); } }
	v_lshlrev_b32_e32 v140, 16, v202
	v_and_b32_e32 v141, 0xffff0000, v202
	v_lshlrev_b32_e32 v142, 16, v203
	v_and_b32_e32 v143, 0xffff0000, v203
	v_lshlrev_b32_e32 v144, 16, v204
	v_and_b32_e32 v145, 0xffff0000, v204
	v_lshlrev_b32_e32 v146, 16, v205
	v_and_b32_e32 v147, 0xffff0000, v205
	v_max_f32_e32 v140, v140, v140
	v_max_f32_e32 v141, v141, v141
	v_max_f32_e32 v142, v142, v142
	v_max_f32_e32 v143, v143, v143
	v_max_f32_e32 v144, v144, v144
	v_max_f32_e32 v145, v145, v145
	v_max_f32_e32 v146, v146, v146
	v_max_f32_e32 v147, v147, v147
	v_max_f32_e32 v140, 0xda24260, v140
	v_max_f32_e32 v141, 0xda24260, v141
	v_max_f32_e32 v142, 0xda24260, v142
	v_max_f32_e32 v143, 0xda24260, v143
	v_max_f32_e32 v144, 0xda24260, v144
	v_max_f32_e32 v145, 0xda24260, v145
	v_max_f32_e32 v146, 0xda24260, v146
	v_max_f32_e32 v147, 0xda24260, v147
	v_rcp_f32_e32 v140, v140
	v_rcp_f32_e32 v141, v141
	v_rcp_f32_e32 v142, v142
	v_rcp_f32_e32 v143, v143
	v_rcp_f32_e32 v144, v144
	v_rcp_f32_e32 v145, v145
	v_rcp_f32_e32 v146, v146
	v_rcp_f32_e32 v147, v147
	v_lshlrev_b32_e32 v154, 16, v178
	v_and_b32_e32 v155, 0xffff0000, v178
	v_lshlrev_b32_e32 v156, 16, v179
	v_and_b32_e32 v157, 0xffff0000, v179
	v_lshlrev_b32_e32 v158, 16, v180
	v_and_b32_e32 v159, 0xffff0000, v180
	v_lshlrev_b32_e32 v160, 16, v181
	v_and_b32_e32 v161, 0xffff0000, v181
	v_pk_mul_f32 v[140:141], v[140:141], v[154:155]
	v_pk_mul_f32 v[142:143], v[142:143], v[156:157]
	v_pk_mul_f32 v[144:145], v[144:145], v[158:159]
	v_pk_mul_f32 v[146:147], v[146:147], v[160:161]
	v_pk_mul_f32 v[52:53], v[52:53], v[140:141]
	v_pk_mul_f32 v[54:55], v[54:55], v[142:143]
	v_pk_mul_f32 v[48:49], v[48:49], v[144:145]
	v_pk_mul_f32 v[50:51], v[50:51], v[146:147]
	s_waitcnt vmcnt(4)
	v_lshlrev_b32_e32 v140, 16, v206
	v_and_b32_e32 v141, 0xffff0000, v206
	v_lshlrev_b32_e32 v142, 16, v207
	v_and_b32_e32 v143, 0xffff0000, v207
	v_lshlrev_b32_e32 v144, 16, v208
	v_and_b32_e32 v145, 0xffff0000, v208
	v_lshlrev_b32_e32 v146, 16, v209
	v_and_b32_e32 v147, 0xffff0000, v209
	v_max_f32_e32 v140, v140, v140
	v_max_f32_e32 v141, v141, v141
	v_max_f32_e32 v142, v142, v142
	v_max_f32_e32 v143, v143, v143
	v_max_f32_e32 v144, v144, v144
	v_max_f32_e32 v145, v145, v145
	v_max_f32_e32 v146, v146, v146
	v_max_f32_e32 v147, v147, v147
	v_max_f32_e32 v140, 0xda24260, v140
	v_max_f32_e32 v141, 0xda24260, v141
	v_max_f32_e32 v142, 0xda24260, v142
	v_max_f32_e32 v143, 0xda24260, v143
	v_max_f32_e32 v144, 0xda24260, v144
	v_max_f32_e32 v145, 0xda24260, v145
	v_max_f32_e32 v146, 0xda24260, v146
	v_max_f32_e32 v147, 0xda24260, v147
	v_rcp_f32_e32 v140, v140
	v_rcp_f32_e32 v141, v141
	v_rcp_f32_e32 v142, v142
	v_rcp_f32_e32 v143, v143
	v_rcp_f32_e32 v144, v144
	v_rcp_f32_e32 v145, v145
	v_rcp_f32_e32 v146, v146
	v_rcp_f32_e32 v147, v147
	v_lshlrev_b32_e32 v154, 16, v182
	v_and_b32_e32 v155, 0xffff0000, v182
	v_lshlrev_b32_e32 v156, 16, v183
	v_and_b32_e32 v157, 0xffff0000, v183
	v_lshlrev_b32_e32 v158, 16, v184
	v_and_b32_e32 v159, 0xffff0000, v184
	v_lshlrev_b32_e32 v160, 16, v185
	v_and_b32_e32 v161, 0xffff0000, v185
	v_pk_mul_f32 v[140:141], v[140:141], v[154:155]
	v_pk_mul_f32 v[142:143], v[142:143], v[156:157]
	v_pk_mul_f32 v[144:145], v[144:145], v[158:159]
	v_pk_mul_f32 v[146:147], v[146:147], v[160:161]
	v_pk_mul_f32 v[20:21], v[20:21], v[140:141]
	v_pk_mul_f32 v[22:23], v[22:23], v[142:143]
	v_pk_mul_f32 v[16:17], v[16:17], v[144:145]
	v_pk_mul_f32 v[18:19], v[18:19], v[146:147]
	s_waitcnt vmcnt(3)
	v_lshlrev_b32_e32 v140, 16, v210
	v_and_b32_e32 v141, 0xffff0000, v210
	v_lshlrev_b32_e32 v142, 16, v211
	v_and_b32_e32 v143, 0xffff0000, v211
	v_lshlrev_b32_e32 v144, 16, v212
	v_and_b32_e32 v145, 0xffff0000, v212
	v_lshlrev_b32_e32 v146, 16, v213
	v_and_b32_e32 v147, 0xffff0000, v213
	v_max_f32_e32 v140, v140, v140
	v_max_f32_e32 v141, v141, v141
	v_max_f32_e32 v142, v142, v142
	v_max_f32_e32 v143, v143, v143
	v_max_f32_e32 v144, v144, v144
	v_max_f32_e32 v145, v145, v145
	v_max_f32_e32 v146, v146, v146
	v_max_f32_e32 v147, v147, v147
	v_max_f32_e32 v140, 0xda24260, v140
	v_max_f32_e32 v141, 0xda24260, v141
	v_max_f32_e32 v142, 0xda24260, v142
	v_max_f32_e32 v143, 0xda24260, v143
	v_max_f32_e32 v144, 0xda24260, v144
	v_max_f32_e32 v145, 0xda24260, v145
	v_max_f32_e32 v146, 0xda24260, v146
	v_max_f32_e32 v147, 0xda24260, v147
	v_rcp_f32_e32 v140, v140
	v_rcp_f32_e32 v141, v141
	v_rcp_f32_e32 v142, v142
	v_rcp_f32_e32 v143, v143
	v_rcp_f32_e32 v144, v144
	v_rcp_f32_e32 v145, v145
	v_rcp_f32_e32 v146, v146
	v_rcp_f32_e32 v147, v147
	v_lshlrev_b32_e32 v154, 16, v186
	v_and_b32_e32 v155, 0xffff0000, v186
	v_lshlrev_b32_e32 v156, 16, v187
	v_and_b32_e32 v157, 0xffff0000, v187
	v_lshlrev_b32_e32 v158, 16, v188
	v_and_b32_e32 v159, 0xffff0000, v188
	v_lshlrev_b32_e32 v160, 16, v189
	v_and_b32_e32 v161, 0xffff0000, v189
	v_pk_mul_f32 v[140:141], v[140:141], v[154:155]
	v_pk_mul_f32 v[142:143], v[142:143], v[156:157]
	v_pk_mul_f32 v[144:145], v[144:145], v[158:159]
	v_pk_mul_f32 v[146:147], v[146:147], v[160:161]
	v_pk_mul_f32 v[44:45], v[44:45], v[140:141]
	v_pk_mul_f32 v[46:47], v[46:47], v[142:143]
	v_pk_mul_f32 v[40:41], v[40:41], v[144:145]
	v_pk_mul_f32 v[42:43], v[42:43], v[146:147]
	s_waitcnt vmcnt(2)
; __device__ __forceinline__ void unpack8(const u32x4 w, f32x4& lo, f32x4& hi) { lo = (f32x4){bf_lo(w.x), bf_hi(w.x), bf_lo(w.y), bf_hi(w.y)}; hi = (f32x4){bf_lo(w.z), bf_hi(w.z), bf_lo(w.w), bf_hi(w.w)}; }
;     __device__ __forceinline__ void operator()(AccT& acc, const Unit& u, int wr, int wc, int fr, int fq) const {
;     ...
;                 for (int bj = 0; bj < 2; ++bj) { f32x4 p0, p1; unpack8(*(const u32x4*)(PROJ + row * DIN + 8192 + col0 + bj * 128), p0, p1);
; #pragma unroll
;                     for (int j = 0; j < 4; ++j) { p0[j] = fmaxf(p0[j], TINY); p1[j] = fmaxf(p1[j], TINY); }
;                     if (u.kind == 0) { f32x4 s0, s1; unpack8(*(const u32x4*)(PROJ + row * DIN + 4096 + col0 + bj * 128), s0, s1);
; #pragma unroll
;                         for (int j = 0; j < 4; ++j) { acc[ai][bj][m][0][j] *= s0[j] * __builtin_amdgcn_rcpf(p0[j]); acc[ai][bj][m][1][j] *= s1[j] * __builtin_amdgcn_rcpf(p1[j]); } }
	v_lshlrev_b32_e32 v140, 16, v214
	v_and_b32_e32 v141, 0xffff0000, v214
	v_lshlrev_b32_e32 v142, 16, v215
	v_and_b32_e32 v143, 0xffff0000, v215
	v_lshlrev_b32_e32 v144, 16, v216
	v_and_b32_e32 v145, 0xffff0000, v216
	v_lshlrev_b32_e32 v146, 16, v217
	v_and_b32_e32 v147, 0xffff0000, v217
	v_max_f32_e32 v140, v140, v140
	v_max_f32_e32 v141, v141, v141
	v_max_f32_e32 v142, v142, v142
	v_max_f32_e32 v143, v143, v143
	v_max_f32_e32 v144, v144, v144
	v_max_f32_e32 v145, v145, v145
	v_max_f32_e32 v146, v146, v146
	v_max_f32_e32 v147, v147, v147
	v_max_f32_e32 v140, 0xda24260, v140
	v_max_f32_e32 v141, 0xda24260, v141
	v_max_f32_e32 v142, 0xda24260, v142
	v_max_f32_e32 v143, 0xda24260, v143
	v_max_f32_e32 v144, 0xda24260, v144
	v_max_f32_e32 v145, 0xda24260, v145
	v_max_f32_e32 v146, 0xda24260, v146
	v_max_f32_e32 v147, 0xda24260, v147
	v_rcp_f32_e32 v140, v140
	v_rcp_f32_e32 v141, v141
	v_rcp_f32_e32 v142, v142
	v_rcp_f32_e32 v143, v143
	v_rcp_f32_e32 v144, v144
	v_rcp_f32_e32 v145, v145
	v_rcp_f32_e32 v146, v146
	v_rcp_f32_e32 v147, v147
	v_lshlrev_b32_e32 v154, 16, v190
	v_and_b32_e32 v155, 0xffff0000, v190
	v_lshlrev_b32_e32 v156, 16, v191
	v_and_b32_e32 v157, 0xffff0000, v191
	v_lshlrev_b32_e32 v158, 16, v192
	v_and_b32_e32 v159, 0xffff0000, v192
	v_lshlrev_b32_e32 v160, 16, v193
	v_and_b32_e32 v161, 0xffff0000, v193
	v_pk_mul_f32 v[140:141], v[140:141], v[154:155]
	v_pk_mul_f32 v[142:143], v[142:143], v[156:157]
	v_pk_mul_f32 v[144:145], v[144:145], v[158:159]
	v_pk_mul_f32 v[146:147], v[146:147], v[160:161]
	v_pk_mul_f32 v[12:13], v[12:13], v[140:141]
	v_pk_mul_f32 v[14:15], v[14:15], v[142:143]
	v_pk_mul_f32 v[8:9], v[8:9], v[144:145]
	v_pk_mul_f32 v[10:11], v[10:11], v[146:147]
	s_waitcnt vmcnt(1)
	v_lshlrev_b32_e32 v140, 16, v218
	v_and_b32_e32 v141, 0xffff0000, v218
	v_lshlrev_b32_e32 v142, 16, v219
	v_and_b32_e32 v143, 0xffff0000, v219
	v_lshlrev_b32_e32 v144, 16, v220
	v_and_b32_e32 v145, 0xffff0000, v220
	v_lshlrev_b32_e32 v146, 16, v221
	v_and_b32_e32 v147, 0xffff0000, v221
	v_max_f32_e32 v140, v140, v140
	v_max_f32_e32 v141, v141, v141
	v_max_f32_e32 v142, v142, v142
	v_max_f32_e32 v143, v143, v143
	v_max_f32_e32 v144, v144, v144
	v_max_f32_e32 v145, v145, v145
	v_max_f32_e32 v146, v146, v146
	v_max_f32_e32 v147, v147, v147
	v_max_f32_e32 v140, 0xda24260, v140
	v_max_f32_e32 v141, 0xda24260, v141
	v_max_f32_e32 v142, 0xda24260, v142
	v_max_f32_e32 v143, 0xda24260, v143
	v_max_f32_e32 v144, 0xda24260, v144
	v_max_f32_e32 v145, 0xda24260, v145
	v_max_f32_e32 v146, 0xda24260, v146
	v_max_f32_e32 v147, 0xda24260, v147
	v_rcp_f32_e32 v140, v140
	v_rcp_f32_e32 v141, v141
	v_rcp_f32_e32 v142, v142
	v_rcp_f32_e32 v143, v143
	v_rcp_f32_e32 v144, v144
	v_rcp_f32_e32 v145, v145
	v_rcp_f32_e32 v146, v146
	v_rcp_f32_e32 v147, v147
	v_lshlrev_b32_e32 v154, 16, v194
	v_and_b32_e32 v155, 0xffff0000, v194
	v_lshlrev_b32_e32 v156, 16, v195
	v_and_b32_e32 v157, 0xffff0000, v195
	v_lshlrev_b32_e32 v158, 16, v196
	v_and_b32_e32 v159, 0xffff0000, v196
	v_lshlrev_b32_e32 v160, 16, v197
	v_and_b32_e32 v161, 0xffff0000, v197
	v_pk_mul_f32 v[140:141], v[140:141], v[154:155]
	v_pk_mul_f32 v[142:143], v[142:143], v[156:157]
	v_pk_mul_f32 v[144:145], v[144:145], v[158:159]
	v_pk_mul_f32 v[146:147], v[146:147], v[160:161]
	v_pk_mul_f32 v[36:37], v[36:37], v[140:141]
	v_pk_mul_f32 v[38:39], v[38:39], v[142:143]
	v_pk_mul_f32 v[32:33], v[32:33], v[144:145]
	v_pk_mul_f32 v[34:35], v[34:35], v[146:147]
	s_waitcnt vmcnt(0)
	v_lshlrev_b32_e32 v140, 16, v222
	v_and_b32_e32 v141, 0xffff0000, v222
	v_lshlrev_b32_e32 v142, 16, v223
	v_and_b32_e32 v143, 0xffff0000, v223
	v_lshlrev_b32_e32 v144, 16, v224
	v_and_b32_e32 v145, 0xffff0000, v224
	v_lshlrev_b32_e32 v146, 16, v225
	v_and_b32_e32 v147, 0xffff0000, v225
	v_max_f32_e32 v140, v140, v140
	v_max_f32_e32 v141, v141, v141
	v_max_f32_e32 v142, v142, v142
	v_max_f32_e32 v143, v143, v143
	v_max_f32_e32 v144, v144, v144
	v_max_f32_e32 v145, v145, v145
	v_max_f32_e32 v146, v146, v146
	v_max_f32_e32 v147, v147, v147
	v_max_f32_e32 v140, 0xda24260, v140
	v_max_f32_e32 v141, 0xda24260, v141
	v_max_f32_e32 v142, 0xda24260, v142
	v_max_f32_e32 v143, 0xda24260, v143
	v_max_f32_e32 v144, 0xda24260, v144
	v_max_f32_e32 v145, 0xda24260, v145
	v_max_f32_e32 v146, 0xda24260, v146
	v_max_f32_e32 v147, 0xda24260, v147
	v_rcp_f32_e32 v140, v140
	v_rcp_f32_e32 v141, v141
	v_rcp_f32_e32 v142, v142
	v_rcp_f32_e32 v143, v143
	v_rcp_f32_e32 v144, v144
	v_rcp_f32_e32 v145, v145
	v_rcp_f32_e32 v146, v146
	v_rcp_f32_e32 v147, v147
	v_lshlrev_b32_e32 v154, 16, v198
	v_and_b32_e32 v155, 0xffff0000, v198
	v_lshlrev_b32_e32 v156, 16, v199
	v_and_b32_e32 v157, 0xffff0000, v199
	v_lshlrev_b32_e32 v158, 16, v200
	v_and_b32_e32 v159, 0xffff0000, v200
	v_lshlrev_b32_e32 v160, 16, v201
	v_and_b32_e32 v161, 0xffff0000, v201
	v_pk_mul_f32 v[140:141], v[140:141], v[154:155]
	v_pk_mul_f32 v[142:143], v[142:143], v[156:157]
	v_pk_mul_f32 v[144:145], v[144:145], v[158:159]
	v_pk_mul_f32 v[146:147], v[146:147], v[160:161]
	v_pk_mul_f32 v[4:5], v[4:5], v[140:141]
	v_pk_mul_f32 v[6:7], v[6:7], v[142:143]
	v_pk_mul_f32 v[0:1], v[0:1], v[144:145]
	v_pk_mul_f32 v[2:3], v[2:3], v[146:147]
	s_branch .Lbr_done
